# mode-0 and mode-1 rwkv chunk scans rewritten (prefetched loads, decay folded into operands); outstanding VMEM ops kept under 64
# baseline (speedup 1.0000x reference)
; template <int MODE> __device__ __forceinline__ void rwkv_item(const Params& P, int e, int c, int h, LAS float* slab, int lane) {
;     ...
;     const int ch = h * 64 + lane;
;     const float mu_r = P.in[I_AMU][(size_t)e * DINA + ch], mu_k = P.in[I_AMU][(size_t)e * DINA + 512 + ch];
;     const float kkw = P.in[I_AKK][e * 512 + ch], ka = P.in[I_AKA][e * 512 + ch], rk = P.in[I_ARK][e * 512 + ch];
;     const float lnw = P.in[I_ALNW][e * 512 + ch], lnb = P.in[I_ALNB][e * 512 + ch];
;     constexpr int SB = MODE == 0 ? 4 : 8;
;     f32x2 S2[32], C2[MODE == 0 ? 32 : 1];
;     const size_t rowoff = (((size_t)c * 8 + h) * 64 + lane) * 64;
;     if (MODE == 0) {
; #pragma unroll
;         for (int i = 0; i < 32; ++i) { S2[i] = (f32x2){(2 * i) == lane ? 1.f : 0.f, (2 * i + 1) == lane ? 1.f : 0.f}; C2[i] = (f32x2){0.f, 0.f}; }
;     } else {
; #pragma unroll
;         for (int q = 0; q < 16; ++q) { const f32x4 v = *(const f32x4*)(MCC + rowoff + 4 * q); S2[2 * q] = (f32x2){v.x, v.y}; S2[2 * q + 1] = (f32x2){v.z, v.w}; }
;     }
;     float r1[SB + 1], k1[SB + 1], vv[SB], dd[SB], aa[SB], gg[MODE == 1 ? SB : 1];
;     ...
;     if (MODE == 1) RW_LOAD(c * RLCH);
.LBB0_205:
	s_and_b32 s0, s2, 7
	s_lshl_b32 s0, s0, 6
	v_readlane_b32 s1, v255, 8
	v_or_b32_e32 v114, s0, v64
	v_lshlrev_b32_e32 v115, 2, v114
	global_load_dword v111, v115, s[26:27]
	global_load_dword v116, v115, s[26:27] offset:2048
	v_or_b32_e32 v122, s1, v114
	v_lshlrev_b32_e32 v122, 2, v122
	global_load_dword v117, v122, s[12:13]
	global_load_dword v118, v122, s[14:15]
	global_load_dword v119, v122, s[16:17]
	global_load_dword v120, v122, s[18:19]
	global_load_dword v121, v122, s[72:73]
	s_lshl_b32 s0, s2, 6
	v_or_b32_e32 v123, s0, v64
	v_lshlrev_b32_e32 v123, 8, v123
	global_load_dwordx4 v[0:3], v123, s[6:7]
	global_load_dwordx4 v[4:7], v123, s[6:7] offset:16
	global_load_dwordx4 v[8:11], v123, s[6:7] offset:32
	global_load_dwordx4 v[12:15], v123, s[6:7] offset:48
	global_load_dwordx4 v[16:19], v123, s[6:7] offset:64
	global_load_dwordx4 v[20:23], v123, s[6:7] offset:80
	global_load_dwordx4 v[24:27], v123, s[6:7] offset:96
	global_load_dwordx4 v[28:31], v123, s[6:7] offset:112
	global_load_dwordx4 v[32:35], v123, s[6:7] offset:128
	global_load_dwordx4 v[36:39], v123, s[6:7] offset:144
	global_load_dwordx4 v[40:43], v123, s[6:7] offset:160
	global_load_dwordx4 v[44:47], v123, s[6:7] offset:176
	global_load_dwordx4 v[48:51], v123, s[6:7] offset:192
	global_load_dwordx4 v[52:55], v123, s[6:7] offset:208
	global_load_dwordx4 v[56:59], v123, s[6:7] offset:224
	global_load_dwordx4 v[60:63], v123, s[6:7] offset:240
	s_ashr_i32 s0, s2, 3
	s_lshl_b32 s1, s0, 6
	s_mul_i32 s8, s1, 0xe00
	v_lshl_add_u32 v108, v114, 1, s8
	s_lshl_b32 s8, s1, 10
	v_lshl_add_u32 v110, v114, 1, s8
	s_lshl_b32 s8, s1, 11
	v_lshl_add_u32 v112, v114, 2, s8
	v_lshl_add_u32 v113, v114, 1, s8
	s_cmp_eq_u32 s0, 0
	s_cselect_b32 s8, 0, 0xe00
	v_subrev_u32_e32 v115, s8, v108
	global_load_ushort v105, v115, s[52:53]
	global_load_ushort v106, v115, s[52:53] offset:1024
	s_waitcnt vmcnt(15)
	global_load_ushort v65, v108, s[52:53]
	global_load_ushort v73, v108, s[52:53] offset:1024
	v_add_u32_e32 v115, 0xe00, v108
	global_load_ushort v66, v115, s[52:53]
	global_load_ushort v74, v115, s[52:53] offset:1024
	v_add_u32_e32 v122, 0x1c00, v108
	global_load_ushort v67, v122, s[52:53]
	global_load_ushort v75, v122, s[52:53] offset:1024
	v_add_u32_e32 v123, 0x2a00, v108
	global_load_ushort v68, v123, s[52:53]
	global_load_ushort v76, v123, s[52:53] offset:1024
	v_add_u32_e32 v114, 0x3800, v108
	global_load_ushort v69, v114, s[52:53]
	global_load_ushort v77, v114, s[52:53] offset:1024
	v_add_u32_e32 v115, 0x4600, v108
	global_load_ushort v70, v115, s[52:53]
	global_load_ushort v78, v115, s[52:53] offset:1024
	v_add_u32_e32 v122, 0x5400, v108
	global_load_ushort v71, v122, s[52:53]
	global_load_ushort v79, v122, s[52:53] offset:1024
	v_add_u32_e32 v123, 0x6200, v108
	global_load_ushort v72, v123, s[52:53]
	global_load_ushort v80, v123, s[52:53] offset:1024
	v_add_u32_e32 v114, 0x1000, v110
	global_load_ushort v81, v110, s[66:67]
	global_load_ushort v82, v110, s[66:67] offset:1024
	global_load_ushort v83, v110, s[66:67] offset:2048
	global_load_ushort v84, v110, s[66:67] offset:3072
	global_load_ushort v85, v114, s[66:67]
	global_load_ushort v86, v114, s[66:67] offset:1024
	global_load_ushort v87, v114, s[66:67] offset:2048
	global_load_ushort v88, v114, s[66:67] offset:3072
	global_load_ushort v97, v110, s[4:5]
	global_load_ushort v98, v110, s[4:5] offset:1024
	global_load_ushort v99, v110, s[4:5] offset:2048
	global_load_ushort v100, v110, s[4:5] offset:3072
	global_load_ushort v101, v114, s[4:5]
	global_load_ushort v102, v114, s[4:5] offset:1024
	global_load_ushort v103, v114, s[4:5] offset:2048
	global_load_ushort v104, v114, s[4:5] offset:3072
	global_load_ushort v167, v110, s[50:51]
	global_load_ushort v168, v110, s[50:51] offset:1024
	global_load_ushort v169, v110, s[50:51] offset:2048
	global_load_ushort v170, v110, s[50:51] offset:3072
	global_load_ushort v171, v114, s[50:51]
	global_load_ushort v172, v114, s[50:51] offset:1024
	global_load_ushort v173, v114, s[50:51] offset:2048
	global_load_ushort v174, v114, s[50:51] offset:3072
	v_add_u32_e32 v115, 0x1000, v112
	v_add_u32_e32 v122, 0x2000, v112
	v_add_u32_e32 v123, 0x3000, v112
	global_load_dword v89, v112, s[46:47]
	global_load_dword v90, v112, s[46:47] offset:2048
	global_load_dword v91, v115, s[46:47]
	global_load_dword v92, v115, s[46:47] offset:2048
	global_load_dword v93, v122, s[46:47]
	global_load_dword v94, v122, s[46:47] offset:2048
	global_load_dword v95, v123, s[46:47]
	global_load_dword v96, v123, s[46:47] offset:2048
	v_add_u32_e32 v108, 0x7000, v108
	v_add_u32_e32 v110, 0x2000, v110
	v_add_u32_e32 v112, 0x4000, v112
	v_mov_b32_e32 v107, 1.0
	s_cmp_gt_i32 s0, 0
	s_cselect_b64 vcc, -1, 0
	s_mov_b32 s1, 0
	s_waitcnt vmcnt(0)
	v_lshlrev_b32_e32 v105, 16, v105
	v_lshlrev_b32_e32 v106, 16, v106
	v_cndmask_b32_e32 v105, 0, v105, vcc
	v_cndmask_b32_e32 v106, 0, v106, vcc
	s_branch .Lm1_prep

; template <int MODE> __device__ __forceinline__ void rwkv_item(const Params& P, int e, int c, int h, LAS float* slab, int lane) {
;     ...
;     const int ch = h * 64 + lane;
;     const float mu_r = P.in[I_AMU][(size_t)e * DINA + ch], mu_k = P.in[I_AMU][(size_t)e * DINA + 512 + ch];
;     const float kkw = P.in[I_AKK][e * 512 + ch], ka = P.in[I_AKA][e * 512 + ch], rk = P.in[I_ARK][e * 512 + ch];
;     const float lnw = P.in[I_ALNW][e * 512 + ch], lnb = P.in[I_ALNB][e * 512 + ch];
;     constexpr int SB = MODE == 0 ? 4 : 8;
;     f32x2 S2[32], C2[MODE == 0 ? 32 : 1];
;     const size_t rowoff = (((size_t)c * 8 + h) * 64 + lane) * 64;
;     if (MODE == 0) {
; #pragma unroll
;         for (int i = 0; i < 32; ++i) { S2[i] = (f32x2){(2 * i) == lane ? 1.f : 0.f, (2 * i + 1) == lane ? 1.f : 0.f}; C2[i] = (f32x2){0.f, 0.f}; }
.LBB0_262:
	s_and_b32 s22, s20, 7
	s_lshl_b32 s22, s22, 6
	s_ashr_i32 s0, s20, 3
	s_lshl_b32 s1, s0, 6
	v_readlane_b32 s2, v255, 8
	v_or_b32_e32 v210, s22, v128
	v_lshlrev_b32_e32 v207, 2, v210
	global_load_dword v230, v207, s[12:13] offset:2048
	v_or_b32_e32 v204, s2, v210
	v_lshlrev_b32_e32 v204, 2, v204
	global_load_dword v231, v204, s[4:5]
	global_load_dword v232, v204, s[6:7]
	s_mul_i32 s2, s1, 0xe00
	s_add_i32 s2, s2, 0x400
	v_lshl_add_u32 v201, v210, 1, s2
	s_lshl_b32 s2, s1, 10
	v_lshl_add_u32 v202, v210, 1, s2
	s_lshl_b32 s2, s1, 11
	v_lshl_add_u32 v203, v210, 2, s2
	s_cmp_eq_u32 s0, 0
	s_cselect_b32 s2, 0, 0xe00
	v_subrev_u32_e32 v204, s2, v201
	global_load_ushort v200, v204, s[26:27]
	s_waitcnt vmcnt(24)
	global_load_ushort v168, v201, s[26:27]
	global_load_ushort v169, v201, s[26:27] offset:3584
	v_add_u32_e32 v204, 0x1c00, v201
	v_add_u32_e32 v205, 0x3800, v201
	v_add_u32_e32 v206, 0x5400, v201
	global_load_ushort v170, v204, s[26:27]
	global_load_ushort v171, v204, s[26:27] offset:3584
	global_load_ushort v172, v205, s[26:27]
	global_load_ushort v173, v205, s[26:27] offset:3584
	global_load_ushort v174, v206, s[26:27]
	global_load_ushort v175, v206, s[26:27] offset:3584
	v_add_u32_e32 v204, 0x1000, v202
	global_load_ushort v176, v202, s[14:15]
	global_load_ushort v177, v202, s[14:15] offset:1024
	global_load_ushort v178, v202, s[14:15] offset:2048
	global_load_ushort v179, v202, s[14:15] offset:3072
	global_load_ushort v180, v204, s[14:15]
	global_load_ushort v181, v204, s[14:15] offset:1024
	global_load_ushort v182, v204, s[14:15] offset:2048
	global_load_ushort v183, v204, s[14:15] offset:3072
	global_load_ushort v192, v202, s[16:17]
	global_load_ushort v193, v202, s[16:17] offset:1024
	global_load_ushort v194, v202, s[16:17] offset:2048
	global_load_ushort v195, v202, s[16:17] offset:3072
	global_load_ushort v196, v204, s[16:17]
	global_load_ushort v197, v204, s[16:17] offset:1024
	global_load_ushort v198, v204, s[16:17] offset:2048
	global_load_ushort v199, v204, s[16:17] offset:3072
	v_add_u32_e32 v205, 0x1000, v203
	v_add_u32_e32 v206, 0x2000, v203
	v_add_u32_e32 v207, 0x3000, v203
	global_load_dword v184, v203, s[10:11]
	global_load_dword v185, v203, s[10:11] offset:2048
	global_load_dword v186, v205, s[10:11]
	global_load_dword v187, v205, s[10:11] offset:2048
	global_load_dword v188, v206, s[10:11]
	global_load_dword v189, v206, s[10:11] offset:2048
	global_load_dword v190, v207, s[10:11]
	global_load_dword v191, v207, s[10:11] offset:2048
	v_add_u32_e32 v201, 0x7000, v201
	v_add_u32_e32 v202, 0x2000, v202
	v_add_u32_e32 v203, 0x4000, v203
	v_cmp_eq_u32_e32 vcc, 0, v128
	v_mov_b32_e32 v124, 0
	s_nop 0
	v_cndmask_b32_e64 v112, 0, 1.0, vcc
	v_cmp_eq_u32_e32 vcc, 1, v128
	v_mov_b32_e32 v125, 0
	s_nop 0
	v_cndmask_b32_e64 v113, 0, 1.0, vcc
	v_cmp_eq_u32_e32 vcc, 2, v128
	v_mov_b32_e32 v126, 0
	s_nop 0
	v_cndmask_b32_e64 v114, 0, 1.0, vcc
	v_cmp_eq_u32_e32 vcc, 3, v128
	v_mov_b32_e32 v127, 0
	s_nop 0
	v_cndmask_b32_e64 v115, 0, 1.0, vcc
	v_cmp_eq_u32_e32 vcc, 4, v128
	v_mov_b32_e32 v120, 0
	s_nop 0
	v_cndmask_b32_e64 v104, 0, 1.0, vcc
	v_cmp_eq_u32_e32 vcc, 5, v128
	v_mov_b32_e32 v121, 0
	s_nop 0
	v_cndmask_b32_e64 v105, 0, 1.0, vcc
	v_cmp_eq_u32_e32 vcc, 6, v128
	v_mov_b32_e32 v122, 0
	s_nop 0
	v_cndmask_b32_e64 v106, 0, 1.0, vcc
	v_cmp_eq_u32_e32 vcc, 7, v128
	v_mov_b32_e32 v123, 0
	s_nop 0
	v_cndmask_b32_e64 v107, 0, 1.0, vcc
	v_cmp_eq_u32_e32 vcc, 8, v128
	v_mov_b32_e32 v116, 0
	s_nop 0
	v_cndmask_b32_e64 v92, 0, 1.0, vcc
	v_cmp_eq_u32_e32 vcc, 9, v128
	v_mov_b32_e32 v117, 0
	s_nop 0
	v_cndmask_b32_e64 v93, 0, 1.0, vcc
	v_cmp_eq_u32_e32 vcc, 10, v128
	v_mov_b32_e32 v118, 0
	s_nop 0
	v_cndmask_b32_e64 v94, 0, 1.0, vcc
	v_cmp_eq_u32_e32 vcc, 11, v128
	v_mov_b32_e32 v119, 0
	s_nop 0
	v_cndmask_b32_e64 v95, 0, 1.0, vcc
	v_cmp_eq_u32_e32 vcc, 12, v128
	v_mov_b32_e32 v108, 0
	s_nop 0
	v_cndmask_b32_e64 v76, 0, 1.0, vcc
	v_cmp_eq_u32_e32 vcc, 13, v128
	v_mov_b32_e32 v109, 0
	s_nop 0
	v_cndmask_b32_e64 v77, 0, 1.0, vcc
	v_cmp_eq_u32_e32 vcc, 14, v128
	v_mov_b32_e32 v110, 0
	s_nop 0
	v_cndmask_b32_e64 v78, 0, 1.0, vcc
	v_cmp_eq_u32_e32 vcc, 15, v128
	v_mov_b32_e32 v111, 0
	s_nop 0
	v_cndmask_b32_e64 v79, 0, 1.0, vcc
	v_cmp_eq_u32_e32 vcc, 16, v128
	v_mov_b32_e32 v96, 0
	s_nop 0
	v_cndmask_b32_e64 v64, 0, 1.0, vcc
	v_cmp_eq_u32_e32 vcc, 17, v128
	v_mov_b32_e32 v97, 0
	s_nop 0
	v_cndmask_b32_e64 v65, 0, 1.0, vcc
	v_cmp_eq_u32_e32 vcc, 18, v128
	v_mov_b32_e32 v98, 0
	s_nop 0
	v_cndmask_b32_e64 v66, 0, 1.0, vcc
	v_cmp_eq_u32_e32 vcc, 19, v128
	v_mov_b32_e32 v99, 0
	s_nop 0
; template <int MODE> __device__ __forceinline__ void rwkv_item(const Params& P, int e, int c, int h, LAS float* slab, int lane) {
;     ...
;     if (MODE == 0) {
; #pragma unroll
;         for (int i = 0; i < 32; ++i) { S2[i] = (f32x2){(2 * i) == lane ? 1.f : 0.f, (2 * i + 1) == lane ? 1.f : 0.f}; C2[i] = (f32x2){0.f, 0.f}; }
	v_cndmask_b32_e64 v67, 0, 1.0, vcc
	v_cmp_eq_u32_e32 vcc, 20, v128
	v_mov_b32_e32 v80, 0
	s_nop 0
	v_cndmask_b32_e64 v100, 0, 1.0, vcc
	v_cmp_eq_u32_e32 vcc, 21, v128
	v_mov_b32_e32 v81, 0
	s_nop 0
	v_cndmask_b32_e64 v101, 0, 1.0, vcc
	v_cmp_eq_u32_e32 vcc, 22, v128
	v_mov_b32_e32 v82, 0
	s_nop 0
	v_cndmask_b32_e64 v102, 0, 1.0, vcc
	v_cmp_eq_u32_e32 vcc, 23, v128
	v_mov_b32_e32 v83, 0
	s_nop 0
	v_cndmask_b32_e64 v103, 0, 1.0, vcc
	v_cmp_eq_u32_e32 vcc, 24, v128
	v_mov_b32_e32 v68, 0
	s_nop 0
	v_cndmask_b32_e64 v88, 0, 1.0, vcc
	v_cmp_eq_u32_e32 vcc, 25, v128
	v_mov_b32_e32 v69, 0
	s_nop 0
	v_cndmask_b32_e64 v89, 0, 1.0, vcc
	v_cmp_eq_u32_e32 vcc, 26, v128
	v_mov_b32_e32 v70, 0
	s_nop 0
	v_cndmask_b32_e64 v90, 0, 1.0, vcc
	v_cmp_eq_u32_e32 vcc, 27, v128
	v_mov_b32_e32 v71, 0
	s_nop 0
	v_cndmask_b32_e64 v91, 0, 1.0, vcc
	v_cmp_eq_u32_e32 vcc, 28, v128
	v_mov_b32_e32 v52, 0
	s_nop 0
	v_cndmask_b32_e64 v84, 0, 1.0, vcc
	v_cmp_eq_u32_e32 vcc, 29, v128
	v_mov_b32_e32 v53, 0
	s_nop 0
	v_cndmask_b32_e64 v85, 0, 1.0, vcc
	v_cmp_eq_u32_e32 vcc, 30, v128
	v_mov_b32_e32 v54, 0
	s_nop 0
	v_cndmask_b32_e64 v86, 0, 1.0, vcc
	v_cmp_eq_u32_e32 vcc, 31, v128
	v_mov_b32_e32 v55, 0
	s_nop 0
	v_cndmask_b32_e64 v87, 0, 1.0, vcc
	v_cmp_eq_u32_e32 vcc, 32, v128
	v_mov_b32_e32 v44, 0
	s_nop 0
	v_cndmask_b32_e64 v72, 0, 1.0, vcc
	v_cmp_eq_u32_e32 vcc, 33, v128
	v_mov_b32_e32 v45, 0
	s_nop 0
	v_cndmask_b32_e64 v73, 0, 1.0, vcc
	v_cmp_eq_u32_e32 vcc, 34, v128
	v_mov_b32_e32 v46, 0
	s_nop 0
	v_cndmask_b32_e64 v74, 0, 1.0, vcc
	v_cmp_eq_u32_e32 vcc, 35, v128
	v_mov_b32_e32 v47, 0
	s_nop 0
	v_cndmask_b32_e64 v75, 0, 1.0, vcc
	v_cmp_eq_u32_e32 vcc, 36, v128
	v_mov_b32_e32 v32, 0
	s_nop 0
	v_cndmask_b32_e64 v60, 0, 1.0, vcc
	v_cmp_eq_u32_e32 vcc, 37, v128
	v_mov_b32_e32 v33, 0
	s_nop 0
	v_cndmask_b32_e64 v61, 0, 1.0, vcc
	v_cmp_eq_u32_e32 vcc, 38, v128
	v_mov_b32_e32 v34, 0
	s_nop 0
	v_cndmask_b32_e64 v62, 0, 1.0, vcc
	v_cmp_eq_u32_e32 vcc, 39, v128
	v_mov_b32_e32 v35, 0
	s_nop 0
	v_cndmask_b32_e64 v63, 0, 1.0, vcc
	v_cmp_eq_u32_e32 vcc, 40, v128
	v_mov_b32_e32 v24, 0
	s_nop 0
	v_cndmask_b32_e64 v56, 0, 1.0, vcc
	v_cmp_eq_u32_e32 vcc, 41, v128
	v_mov_b32_e32 v25, 0
	s_nop 0
	v_cndmask_b32_e64 v57, 0, 1.0, vcc
	v_cmp_eq_u32_e32 vcc, 42, v128
	v_mov_b32_e32 v26, 0
	s_nop 0
	v_cndmask_b32_e64 v58, 0, 1.0, vcc
	v_cmp_eq_u32_e32 vcc, 43, v128
	v_mov_b32_e32 v27, 0
	s_nop 0
	v_cndmask_b32_e64 v59, 0, 1.0, vcc
	v_cmp_eq_u32_e32 vcc, 44, v128
	v_mov_b32_e32 v16, 0
	s_nop 0
	v_cndmask_b32_e64 v48, 0, 1.0, vcc
	v_cmp_eq_u32_e32 vcc, 45, v128
	v_mov_b32_e32 v17, 0
	s_nop 0
	v_cndmask_b32_e64 v49, 0, 1.0, vcc
	v_cmp_eq_u32_e32 vcc, 46, v128
	v_mov_b32_e32 v18, 0
	s_nop 0
	v_cndmask_b32_e64 v50, 0, 1.0, vcc
	v_cmp_eq_u32_e32 vcc, 47, v128
	v_mov_b32_e32 v19, 0
	s_nop 0
	v_cndmask_b32_e64 v51, 0, 1.0, vcc
	v_cmp_eq_u32_e32 vcc, 48, v128
	v_mov_b32_e32 v12, 0
	s_nop 0
	v_cndmask_b32_e64 v40, 0, 1.0, vcc
	v_cmp_eq_u32_e32 vcc, 49, v128
	v_mov_b32_e32 v13, 0
	s_nop 0
	v_cndmask_b32_e64 v41, 0, 1.0, vcc
	v_cmp_eq_u32_e32 vcc, 50, v128
	v_mov_b32_e32 v14, 0
	s_nop 0
	v_cndmask_b32_e64 v42, 0, 1.0, vcc
	v_cmp_eq_u32_e32 vcc, 51, v128
	v_mov_b32_e32 v15, 0
	s_nop 0
	v_cndmask_b32_e64 v43, 0, 1.0, vcc
	v_cmp_eq_u32_e32 vcc, 52, v128
	v_mov_b32_e32 v8, 0
	s_nop 0
	v_cndmask_b32_e64 v36, 0, 1.0, vcc
	v_cmp_eq_u32_e32 vcc, 53, v128
	v_mov_b32_e32 v9, 0
	s_nop 0
	v_cndmask_b32_e64 v37, 0, 1.0, vcc
	v_cmp_eq_u32_e32 vcc, 54, v128
	v_mov_b32_e32 v10, 0
	s_nop 0
	v_cndmask_b32_e64 v38, 0, 1.0, vcc
	v_cmp_eq_u32_e32 vcc, 55, v128
	v_mov_b32_e32 v11, 0
	s_nop 0
	v_cndmask_b32_e64 v39, 0, 1.0, vcc
	v_cmp_eq_u32_e32 vcc, 56, v128
	v_mov_b32_e32 v4, 0
	s_nop 0
	v_cndmask_b32_e64 v28, 0, 1.0, vcc
	v_cmp_eq_u32_e32 vcc, 57, v128
	v_mov_b32_e32 v5, 0
	s_nop 0
	v_cndmask_b32_e64 v29, 0, 1.0, vcc
	v_cmp_eq_u32_e32 vcc, 58, v128
	v_mov_b32_e32 v6, 0
	s_nop 0
	v_cndmask_b32_e64 v30, 0, 1.0, vcc
	v_cmp_eq_u32_e32 vcc, 59, v128
	v_mov_b32_e32 v7, 0
	s_nop 0
	v_cndmask_b32_e64 v31, 0, 1.0, vcc
	v_cmp_eq_u32_e32 vcc, 60, v128
	v_mov_b32_e32 v0, 0
	s_nop 0
	v_cndmask_b32_e64 v20, 0, 1.0, vcc
	v_cmp_eq_u32_e32 vcc, 61, v128
	v_mov_b32_e32 v1, 0
	s_nop 0
	v_cndmask_b32_e64 v21, 0, 1.0, vcc
	v_cmp_eq_u32_e32 vcc, 62, v128
	v_mov_b32_e32 v2, 0
	s_nop 0
	v_cndmask_b32_e64 v22, 0, 1.0, vcc
	v_cmp_eq_u32_e32 vcc, 63, v128
	v_mov_b32_e32 v3, 0
	s_nop 0
	v_cndmask_b32_e64 v23, 0, 1.0, vcc
	s_mov_b32 s23, 0
	v_mov_b32_e32 v137, 1.0
	s_cmp_gt_i32 s0, 0
	s_cselect_b64 vcc, -1, 0
	s_waitcnt vmcnt(32)
	v_lshlrev_b32_e32 v200, 16, v200
	v_cndmask_b32_e32 v200, 0, v200, vcc
